# XCD-hierarchical barrier now also replaces cooperative-groups sync 0: block 0 zeroes the barrier page at kernel start and publishes a ready flag; census at sync 0
# speedup vs baseline: 1.0791x; 1.0032x over previous
_Z4mega6Paramsii:
	s_load_dwordx2 s[38:39], s[0:1], 0x490
	s_add_u32 s80, s0, 0x498
	s_addc_u32 s81, s1, 0
	s_load_dword s40, s[0:1], 0x498
	s_load_dwordx2 s[84:85], s[0:1], 0x120
	s_mov_b32 s82, s2
	s_waitcnt lgkmcnt(0)
	s_cmp_lt_i32 s38, 1
	s_cselect_b64 s[16:17], -1, 0
	s_cmp_gt_i32 s38, 0
	s_cselect_b64 s[2:3], -1, 0
	s_cmp_lt_i32 s39, 0
	s_cselect_b64 s[4:5], -1, 0
	s_or_b64 s[2:3], s[2:3], s[4:5]
	s_and_b64 vcc, exec, s[2:3]
	s_cbranch_vccnz .LBB0_89
	s_mov_b64 s[18:19], s[84:85]
	s_cmp_lg_u32 s82, 0
	v_and_b32_e32 v11, 0x3ff, v0
	s_cbranch_scc1 .LBB0_7
	v_lshlrev_b32_e32 v1, 2, v11
	v_mov_b32_e32 v2, 0
	s_add_u32 s98, s84, 0x2ce10000
	s_addc_u32 s99, s85, 0
	global_store_dword v1, v2, s[98:99]
	global_store_dword v1, v2, s[98:99] offset:1024
	global_store_dword v1, v2, s[98:99] offset:2048
	global_store_dword v1, v2, s[98:99] offset:3072
	s_add_u32 s98, s98, 0x1000
	s_addc_u32 s99, s99, 0
	global_store_dword v1, v2, s[98:99]
	global_store_dword v1, v2, s[98:99] offset:1024
	global_store_dword v1, v2, s[98:99] offset:2048
	global_store_dword v1, v2, s[98:99] offset:3072
	s_add_u32 s98, s98, 0x1000
	s_addc_u32 s99, s99, 0
	global_store_dword v1, v2, s[98:99]
	global_store_dword v1, v2, s[98:99] offset:1024
	global_store_dword v1, v2, s[98:99] offset:2048
	global_store_dword v1, v2, s[98:99] offset:3072
	s_waitcnt vmcnt(0)
	s_barrier
	v_cmp_eq_u32_e32 vcc, 0, v11
	s_and_saveexec_b64 s[100:101], vcc
	buffer_wbl2 sc1
	s_waitcnt vmcnt(0)
	v_mov_b32_e32 v1, 0
	v_mov_b32_e32 v2, 0x6a3d91c7
	s_add_u32 s98, s84, 0x2ce11200
	s_addc_u32 s99, s85, 0
	global_atomic_swap v1, v2, s[98:99]
	s_waitcnt vmcnt(0)
	s_or_b64 exec, exec, s[100:101]
	v_cmp_gt_u32_e32 vcc, 34, v11
	s_and_saveexec_b64 s[4:5], vcc
	s_cbranch_execz .LBB0_4
	v_lshlrev_b32_e32 v2, 3, v11
	global_load_dwordx2 v[4:5], v2, s[0:1]
	v_mov_b32_e32 v3, 0
	v_lshl_add_u64 v[2:3], s[18:19], 0, v[2:3]
	v_add_co_u32_e32 v2, vcc, 0x2d500000, v2
	s_nop 1
	v_addc_co_u32_e32 v3, vcc, 0, v3, vcc
	s_waitcnt vmcnt(0)
	flat_store_dwordx2 v[2:3], v[4:5]

.LBB0_68:
	s_or_b64 exec, exec, s[14:15]
	v_cmp_gt_i32_e32 vcc, 16, v2
	v_ashrrev_i32_e32 v3, 31, v2
	s_and_saveexec_b64 s[4:5], vcc
	s_cbranch_execz .LBB0_70
	v_lshl_add_u64 v[4:5], v[2:3], 2, s[84:85]
	v_add_co_u32_e32 v4, vcc, 0x2ce10000, v4
	v_mov_b32_e32 v1, 0
	s_nop 0
	v_addc_co_u32_e32 v5, vcc, 0, v5, vcc
	global_store_dword v[4:5], v1, off

.LBB0_89:
	s_cmp_gt_i32 s39, 0
	s_cselect_b64 s[0:1], -1, 0
	s_and_b64 s[2:3], s[16:17], s[0:1]
	s_andn2_b64 vcc, exec, s[2:3]
	s_cbranch_vccnz .LBB0_101
	v_and_b32_e32 v1, 0x3fffffff, v0
	v_cmp_eq_u32_e32 vcc, 0, v1
	s_waitcnt vmcnt(0) lgkmcnt(0)
	s_barrier
	s_and_saveexec_b64 s[4:5], vcc
	s_cbranch_execz .LBB0_100
	s_add_u32 s6, s84, 0x2ce12000
	s_addc_u32 s7, s85, 0
	s_getreg_b32 s98, hwreg(HW_REG_XCC_ID, 0, 4)
	s_lshl_b32 s99, s98, 7
	s_lshl_b32 s98, s98, 8
	v_mov_b32_e32 v1, s98
	v_mov_b32_e32 v3, s99
	v_mov_b32_e32 v4, 0
	s_mov_b32 s101, 0x40000
.Lxb_flag:
	global_load_dword v2, v4, s[6:7] offset:-3584 sc1
	s_waitcnt vmcnt(0)
	v_readfirstlane_b32 s100, v2
	s_cmp_eq_u32 s100, 0x6a3d91c7
	s_cbranch_scc1 .Lxb_flag_ok
	s_sleep 1
	s_sub_u32 s101, s101, 1
	s_cmp_lg_u32 s101, 0
	s_cbranch_scc1 .Lxb_flag
.Lxb_flag_ok:
	v_mov_b32_e32 v2, 1
	global_atomic_add v3, v2, s[6:7] offset:-2048
	s_movk_i32 s101, 0x4000

.LBB0_228:
	s_cmp_gt_i32 s39, 1
	s_cselect_b64 s[0:1], -1, 0
	s_and_b64 s[2:3], s[6:7], s[0:1]
	s_andn2_b64 vcc, exec, s[2:3]
	s_cbranch_vccnz .LBB0_240
	v_and_b32_e32 v1, 0x3fffffff, v0
	v_cmp_eq_u32_e32 vcc, 0, v1
	s_waitcnt vmcnt(0) lgkmcnt(0)
	s_barrier
	s_and_saveexec_b64 s[4:5], vcc
	s_cbranch_execz .LBB0_239
	s_add_u32 s6, s84, 0x2ce12000
	s_addc_u32 s7, s85, 0
	s_getreg_b32 s98, hwreg(HW_REG_XCC_ID, 0, 4)
	s_lshl_b32 s99, s98, 7
	s_lshl_b32 s98, s98, 8
	v_mov_b32_e32 v1, s98
	v_mov_b32_e32 v3, s99
	v_mov_b32_e32 v4, 0
	v_mov_b32_e32 v2, 1
	global_load_dword v3, v3, s[6:7] offset:-2048 sc1
	global_atomic_add v4, v1, v2, s[6:7] sc0
	s_waitcnt vmcnt(0)
	v_readfirstlane_b32 s100, v3
	v_readfirstlane_b32 s99, v4
	s_mul_i32 s98, s100, 2
	s_add_i32 s99, s99, 1
	s_cmp_lg_u32 s99, s98
	s_cbranch_scc1 .Lxb_follow_s2
	buffer_wbl2 sc1
	s_waitcnt vmcnt(0)
	v_mov_b32_e32 v4, 0
	global_atomic_add v2, v4, v3, s[6:7] offset:-4096 sc0
	s_waitcnt vmcnt(0)
	v_readfirstlane_b32 s99, v2
	s_add_i32 s99, s99, s100
	s_mul_i32 s98, s40, 2
	v_mov_b32_e32 v2, 1
	s_cmp_lg_u32 s99, s98
	s_cbranch_scc1 .Lxb_topwait_s2
	global_atomic_add v4, v2, s[6:7] offset:-3840
	s_branch .Lxb_topdone_s2

.LBB0_383:
	s_cmp_gt_i32 s39, 2
	v_readlane_b32 s2, v247, 0
	s_cselect_b64 s[0:1], -1, 0
	v_readlane_b32 s3, v247, 1
	s_and_b64 s[2:3], s[2:3], s[0:1]
	s_andn2_b64 vcc, exec, s[2:3]
	s_cbranch_vccnz .LBB0_395
	v_and_b32_e32 v1, 0x3fffffff, v0
	v_cmp_eq_u32_e32 vcc, 0, v1
	s_waitcnt vmcnt(0) lgkmcnt(0)
	s_barrier
	s_and_saveexec_b64 s[4:5], vcc
	s_cbranch_execz .LBB0_394
	s_add_u32 s6, s84, 0x2ce12000
	s_addc_u32 s7, s85, 0
	s_getreg_b32 s98, hwreg(HW_REG_XCC_ID, 0, 4)
	s_lshl_b32 s99, s98, 7
	s_lshl_b32 s98, s98, 8
	v_mov_b32_e32 v1, s98
	v_mov_b32_e32 v3, s99
	v_mov_b32_e32 v4, 0
	v_mov_b32_e32 v2, 1
	global_load_dword v3, v3, s[6:7] offset:-2048 sc1
	global_atomic_add v4, v1, v2, s[6:7] sc0
	s_waitcnt vmcnt(0)
	v_readfirstlane_b32 s100, v3
	v_readfirstlane_b32 s99, v4
	s_mul_i32 s98, s100, 3
	s_add_i32 s99, s99, 1
	s_cmp_lg_u32 s99, s98
	s_cbranch_scc1 .Lxb_follow_s3
	buffer_wbl2 sc1
	s_waitcnt vmcnt(0)
	v_mov_b32_e32 v4, 0
	global_atomic_add v2, v4, v3, s[6:7] offset:-4096 sc0
	s_waitcnt vmcnt(0)
	v_readfirstlane_b32 s99, v2
	s_add_i32 s99, s99, s100
	s_mul_i32 s98, s40, 3
	v_mov_b32_e32 v2, 1
	s_cmp_lg_u32 s99, s98
	s_cbranch_scc1 .Lxb_topwait_s3
	global_atomic_add v4, v2, s[6:7] offset:-3840
	s_branch .Lxb_topdone_s3

.LBB0_494:
	s_cmp_gt_i32 s39, 3
	s_cselect_b64 s[0:1], -1, 0
	s_and_b64 s[2:3], s[12:13], s[0:1]
	s_andn2_b64 vcc, exec, s[2:3]
	s_cbranch_vccnz .LBB0_506
	v_and_b32_e32 v1, 0x3fffffff, v0
	v_cmp_eq_u32_e32 vcc, 0, v1
	s_waitcnt vmcnt(0) lgkmcnt(0)
	s_barrier
	s_and_saveexec_b64 s[4:5], vcc
	s_cbranch_execz .LBB0_505
	s_add_u32 s6, s84, 0x2ce12000
	s_addc_u32 s7, s85, 0
	s_getreg_b32 s98, hwreg(HW_REG_XCC_ID, 0, 4)
	s_lshl_b32 s99, s98, 7
	s_lshl_b32 s98, s98, 8
	v_mov_b32_e32 v1, s98
	v_mov_b32_e32 v3, s99
	v_mov_b32_e32 v4, 0
	v_mov_b32_e32 v2, 1
	global_load_dword v3, v3, s[6:7] offset:-2048 sc1
	global_atomic_add v4, v1, v2, s[6:7] sc0
	s_waitcnt vmcnt(0)
	v_readfirstlane_b32 s100, v3
	v_readfirstlane_b32 s99, v4
	s_mul_i32 s98, s100, 4
	s_add_i32 s99, s99, 1
	s_cmp_lg_u32 s99, s98
	s_cbranch_scc1 .Lxb_follow_s4
	buffer_wbl2 sc1
	s_waitcnt vmcnt(0)
	v_mov_b32_e32 v4, 0
	global_atomic_add v2, v4, v3, s[6:7] offset:-4096 sc0
	s_waitcnt vmcnt(0)
	v_readfirstlane_b32 s99, v2
	s_add_i32 s99, s99, s100
	s_mul_i32 s98, s40, 4
	v_mov_b32_e32 v2, 1
	s_cmp_lg_u32 s99, s98
	s_cbranch_scc1 .Lxb_topwait_s4
	global_atomic_add v4, v2, s[6:7] offset:-3840
	s_branch .Lxb_topdone_s4

.LBB0_514:
	s_cmp_gt_i32 s39, 4
	s_cselect_b64 s[0:1], -1, 0
	s_and_b64 s[2:3], s[16:17], s[0:1]
	s_andn2_b64 vcc, exec, s[2:3]
	s_cbranch_vccnz .LBB0_526
	v_and_b32_e32 v1, 0x3fffffff, v0
	v_cmp_eq_u32_e32 vcc, 0, v1
	s_waitcnt vmcnt(0) lgkmcnt(0)
	s_barrier
	s_and_saveexec_b64 s[4:5], vcc
	s_cbranch_execz .LBB0_525
	s_add_u32 s6, s84, 0x2ce12000
	s_addc_u32 s7, s85, 0
	s_getreg_b32 s98, hwreg(HW_REG_XCC_ID, 0, 4)
	s_lshl_b32 s99, s98, 7
	s_lshl_b32 s98, s98, 8
	v_mov_b32_e32 v1, s98
	v_mov_b32_e32 v3, s99
	v_mov_b32_e32 v4, 0
	v_mov_b32_e32 v2, 1
	global_load_dword v3, v3, s[6:7] offset:-2048 sc1
	global_atomic_add v4, v1, v2, s[6:7] sc0
	s_waitcnt vmcnt(0)
	v_readfirstlane_b32 s100, v3
	v_readfirstlane_b32 s99, v4
	s_mul_i32 s98, s100, 5
	s_add_i32 s99, s99, 1
	s_cmp_lg_u32 s99, s98
	s_cbranch_scc1 .Lxb_follow_s5
	buffer_wbl2 sc1
	s_waitcnt vmcnt(0)
	v_mov_b32_e32 v4, 0
	global_atomic_add v2, v4, v3, s[6:7] offset:-4096 sc0
	s_waitcnt vmcnt(0)
	v_readfirstlane_b32 s99, v2
	s_add_i32 s99, s99, s100
	s_mul_i32 s98, s40, 5
	v_mov_b32_e32 v2, 1
	s_cmp_lg_u32 s99, s98
	s_cbranch_scc1 .Lxb_topwait_s5
	global_atomic_add v4, v2, s[6:7] offset:-3840
	s_branch .Lxb_topdone_s5

.Lxb_topspin_s5:
	global_load_dword v3, v4, s[6:7] offset:-3840 sc1
	s_waitcnt vmcnt(0)
	v_readfirstlane_b32 s99, v3
	s_cmp_ge_u32 s99, 5
	s_cbranch_scc1 .Lxb_topdone_s5
	s_sleep 1
	s_sub_u32 s101, s101, 1
	s_cmp_lg_u32 s101, 0
	s_cbranch_scc1 .Lxb_topspin_s5

.Lxb_spin_s5:
	global_load_dword v3, v1, s[6:7] offset:128 sc1
	s_waitcnt vmcnt(0)
	v_readfirstlane_b32 s99, v3
	s_cmp_ge_u32 s99, 5
	s_cbranch_scc1 .Lxb_rel_s5
	s_sleep 1
	s_sub_u32 s101, s101, 1
	s_cmp_lg_u32 s101, 0
	s_cbranch_scc1 .Lxb_spin_s5

.LBB0_548:
	s_cmp_gt_i32 s39, 5
	s_cselect_b64 s[6:7], -1, 0
	s_and_b64 s[0:1], s[4:5], s[6:7]
	s_andn2_b64 vcc, exec, s[0:1]
	s_cbranch_vccnz .LBB0_560
	v_and_b32_e32 v1, 0x3fffffff, v0
	v_cmp_eq_u32_e32 vcc, 0, v1
	s_waitcnt vmcnt(0) lgkmcnt(0)
	s_barrier
	s_and_saveexec_b64 s[0:1], vcc
	s_cbranch_execz .LBB0_559
	s_add_u32 s4, s84, 0x2ce12000
	s_addc_u32 s5, s85, 0
	s_getreg_b32 s98, hwreg(HW_REG_XCC_ID, 0, 4)
	s_lshl_b32 s99, s98, 7
	s_lshl_b32 s98, s98, 8
	v_mov_b32_e32 v1, s98
	v_mov_b32_e32 v3, s99
	v_mov_b32_e32 v4, 0
	v_mov_b32_e32 v2, 1
	global_load_dword v3, v3, s[4:5] offset:-2048 sc1
	global_atomic_add v4, v1, v2, s[4:5] sc0
	s_waitcnt vmcnt(0)
	v_readfirstlane_b32 s100, v3
	v_readfirstlane_b32 s99, v4
	s_mul_i32 s98, s100, 6
	s_add_i32 s99, s99, 1
	s_cmp_lg_u32 s99, s98
	s_cbranch_scc1 .Lxb_follow_s6
	buffer_wbl2 sc1
	s_waitcnt vmcnt(0)
	v_mov_b32_e32 v4, 0
	global_atomic_add v2, v4, v3, s[4:5] offset:-4096 sc0
	s_waitcnt vmcnt(0)
	v_readfirstlane_b32 s99, v2
	s_add_i32 s99, s99, s100
	s_mul_i32 s98, s40, 6
	v_mov_b32_e32 v2, 1
	s_cmp_lg_u32 s99, s98
	s_cbranch_scc1 .Lxb_topwait_s6
	global_atomic_add v4, v2, s[4:5] offset:-3840
	s_branch .Lxb_topdone_s6

.LBB0_570:
	s_cmp_gt_i32 s39, 6
	s_cselect_b64 s[6:7], -1, 0
	s_and_b64 s[0:1], s[0:1], s[6:7]
	s_andn2_b64 vcc, exec, s[0:1]
	s_cbranch_vccnz .LBB0_582
	v_and_b32_e32 v1, 0x3fffffff, v0
	v_cmp_eq_u32_e32 vcc, 0, v1
	s_waitcnt vmcnt(0) lgkmcnt(0)
	s_barrier
	s_and_saveexec_b64 s[0:1], vcc
	s_cbranch_execz .LBB0_581
	s_add_u32 s4, s84, 0x2ce12000
	s_addc_u32 s5, s85, 0
	s_getreg_b32 s98, hwreg(HW_REG_XCC_ID, 0, 4)
	s_lshl_b32 s99, s98, 7
	s_lshl_b32 s98, s98, 8
	v_mov_b32_e32 v1, s98
	v_mov_b32_e32 v3, s99
	v_mov_b32_e32 v4, 0
	v_mov_b32_e32 v2, 1
	global_load_dword v3, v3, s[4:5] offset:-2048 sc1
	global_atomic_add v4, v1, v2, s[4:5] sc0
	s_waitcnt vmcnt(0)
	v_readfirstlane_b32 s100, v3
	v_readfirstlane_b32 s99, v4
	s_mul_i32 s98, s100, 7
	s_add_i32 s99, s99, 1
	s_cmp_lg_u32 s99, s98
	s_cbranch_scc1 .Lxb_follow_s7
	buffer_wbl2 sc1
	s_waitcnt vmcnt(0)
	v_mov_b32_e32 v4, 0
	global_atomic_add v2, v4, v3, s[4:5] offset:-4096 sc0
	s_waitcnt vmcnt(0)
	v_readfirstlane_b32 s99, v2
	s_add_i32 s99, s99, s100
	s_mul_i32 s98, s40, 7
	v_mov_b32_e32 v2, 1
	s_cmp_lg_u32 s99, s98
	s_cbranch_scc1 .Lxb_topwait_s7
	global_atomic_add v4, v2, s[4:5] offset:-3840
	s_branch .Lxb_topdone_s7

.Lxb_topspin_s7:
	global_load_dword v3, v4, s[4:5] offset:-3840 sc1
	s_waitcnt vmcnt(0)
	v_readfirstlane_b32 s99, v3
	s_cmp_ge_u32 s99, 7
	s_cbranch_scc1 .Lxb_topdone_s7
	s_sleep 1
	s_sub_u32 s101, s101, 1
	s_cmp_lg_u32 s101, 0
	s_cbranch_scc1 .Lxb_topspin_s7

.Lxb_spin_s7:
	global_load_dword v3, v1, s[4:5] offset:128 sc1
	s_waitcnt vmcnt(0)
	v_readfirstlane_b32 s99, v3
	s_cmp_ge_u32 s99, 7
	s_cbranch_scc1 .Lxb_rel_s7
	s_sleep 1
	s_sub_u32 s101, s101, 1
	s_cmp_lg_u32 s101, 0
	s_cbranch_scc1 .Lxb_spin_s7

.LBB0_604:
	s_cmp_gt_i32 s39, 7
	s_cselect_b64 s[0:1], -1, 0
	s_and_b64 s[2:3], s[4:5], s[0:1]
	s_andn2_b64 vcc, exec, s[2:3]
	s_cbranch_vccnz .LBB0_616
	v_and_b32_e32 v1, 0x3fffffff, v0
	v_cmp_eq_u32_e32 vcc, 0, v1
	s_waitcnt vmcnt(0) lgkmcnt(0)
	s_barrier
	s_and_saveexec_b64 s[4:5], vcc
	s_cbranch_execz .LBB0_615
	s_add_u32 s6, s84, 0x2ce12000
	s_addc_u32 s7, s85, 0
	s_getreg_b32 s98, hwreg(HW_REG_XCC_ID, 0, 4)
	s_lshl_b32 s99, s98, 7
	s_lshl_b32 s98, s98, 8
	v_mov_b32_e32 v1, s98
	v_mov_b32_e32 v3, s99
	v_mov_b32_e32 v4, 0
	v_mov_b32_e32 v2, 1
	global_load_dword v3, v3, s[6:7] offset:-2048 sc1
	global_atomic_add v4, v1, v2, s[6:7] sc0
	s_waitcnt vmcnt(0)
	v_readfirstlane_b32 s100, v3
	v_readfirstlane_b32 s99, v4
	s_mul_i32 s98, s100, 8
	s_add_i32 s99, s99, 1
	s_cmp_lg_u32 s99, s98
	s_cbranch_scc1 .Lxb_follow_s8
	buffer_wbl2 sc1
	s_waitcnt vmcnt(0)
	v_mov_b32_e32 v4, 0
	global_atomic_add v2, v4, v3, s[6:7] offset:-4096 sc0
	s_waitcnt vmcnt(0)
	v_readfirstlane_b32 s99, v2
	s_add_i32 s99, s99, s100
	s_mul_i32 s98, s40, 8
	v_mov_b32_e32 v2, 1
	s_cmp_lg_u32 s99, s98
	s_cbranch_scc1 .Lxb_topwait_s8
	global_atomic_add v4, v2, s[6:7] offset:-3840
	s_branch .Lxb_topdone_s8

.LBB0_638:
	s_cmp_gt_i32 s39, 8
	s_cselect_b64 s[0:1], -1, 0
	s_and_b64 s[2:3], s[10:11], s[0:1]
	s_andn2_b64 vcc, exec, s[2:3]
	s_cbranch_vccnz .LBB0_650
	v_and_b32_e32 v1, 0x3fffffff, v0
	v_cmp_eq_u32_e32 vcc, 0, v1
	s_waitcnt vmcnt(0) lgkmcnt(0)
	s_barrier
	s_and_saveexec_b64 s[4:5], vcc
	s_cbranch_execz .LBB0_649
	s_add_u32 s6, s84, 0x2ce12000
	s_addc_u32 s7, s85, 0
	s_getreg_b32 s98, hwreg(HW_REG_XCC_ID, 0, 4)
	s_lshl_b32 s99, s98, 7
	s_lshl_b32 s98, s98, 8
	v_mov_b32_e32 v1, s98
	v_mov_b32_e32 v3, s99
	v_mov_b32_e32 v4, 0
	v_mov_b32_e32 v2, 1
	global_load_dword v3, v3, s[6:7] offset:-2048 sc1
	global_atomic_add v4, v1, v2, s[6:7] sc0
	s_waitcnt vmcnt(0)
	v_readfirstlane_b32 s100, v3
	v_readfirstlane_b32 s99, v4
	s_mul_i32 s98, s100, 9
	s_add_i32 s99, s99, 1
	s_cmp_lg_u32 s99, s98
	s_cbranch_scc1 .Lxb_follow_s9
	buffer_wbl2 sc1
	s_waitcnt vmcnt(0)
	v_mov_b32_e32 v4, 0
	global_atomic_add v2, v4, v3, s[6:7] offset:-4096 sc0
	s_waitcnt vmcnt(0)
	v_readfirstlane_b32 s99, v2
	s_add_i32 s99, s99, s100
	s_mul_i32 s98, s40, 9
	v_mov_b32_e32 v2, 1
	s_cmp_lg_u32 s99, s98
	s_cbranch_scc1 .Lxb_topwait_s9
	global_atomic_add v4, v2, s[6:7] offset:-3840
	s_branch .Lxb_topdone_s9

.LBB0_905:
	s_cmp_gt_i32 s39, 9
	s_cselect_b64 s[0:1], -1, 0
	s_and_b64 s[2:3], s[10:11], s[0:1]
	s_andn2_b64 vcc, exec, s[2:3]
	s_cbranch_vccnz .LBB0_917
	v_and_b32_e32 v1, 0x3fffffff, v0
	v_cmp_eq_u32_e32 vcc, 0, v1
	s_waitcnt vmcnt(0) lgkmcnt(0)
	s_barrier
	s_and_saveexec_b64 s[4:5], vcc
	s_cbranch_execz .LBB0_916
	s_add_u32 s6, s84, 0x2ce12000
	s_addc_u32 s7, s85, 0
	s_getreg_b32 s98, hwreg(HW_REG_XCC_ID, 0, 4)
	s_lshl_b32 s99, s98, 7
	s_lshl_b32 s98, s98, 8
	v_mov_b32_e32 v1, s98
	v_mov_b32_e32 v3, s99
	v_mov_b32_e32 v4, 0
	v_mov_b32_e32 v2, 1
	global_load_dword v3, v3, s[6:7] offset:-2048 sc1
	global_atomic_add v4, v1, v2, s[6:7] sc0
	s_waitcnt vmcnt(0)
	v_readfirstlane_b32 s100, v3
	v_readfirstlane_b32 s99, v4
	s_mul_i32 s98, s100, 10
	s_add_i32 s99, s99, 1
	s_cmp_lg_u32 s99, s98
	s_cbranch_scc1 .Lxb_follow_s10
	buffer_wbl2 sc1
	s_waitcnt vmcnt(0)
	v_mov_b32_e32 v4, 0
	global_atomic_add v2, v4, v3, s[6:7] offset:-4096 sc0
	s_waitcnt vmcnt(0)
	v_readfirstlane_b32 s99, v2
	s_add_i32 s99, s99, s100
	s_mul_i32 s98, s40, 10
	v_mov_b32_e32 v2, 1
	s_cmp_lg_u32 s99, s98
	s_cbranch_scc1 .Lxb_topwait_s10
	global_atomic_add v4, v2, s[6:7] offset:-3840
	s_branch .Lxb_topdone_s10

.LBB0_1087:
	s_cmp_gt_i32 s39, 10
	s_cselect_b64 s[0:1], -1, 0
	s_and_b64 s[2:3], s[4:5], s[0:1]
	s_andn2_b64 vcc, exec, s[2:3]
	s_cbranch_vccnz .LBB0_1099
	v_and_b32_e32 v1, 0x3fffffff, v0
	v_cmp_eq_u32_e32 vcc, 0, v1
	s_waitcnt vmcnt(0) lgkmcnt(0)
	s_barrier
	s_and_saveexec_b64 s[4:5], vcc
	s_cbranch_execz .LBB0_1098
	s_add_u32 s6, s84, 0x2ce12000
	s_addc_u32 s7, s85, 0
	s_getreg_b32 s98, hwreg(HW_REG_XCC_ID, 0, 4)
	s_lshl_b32 s99, s98, 7
	s_lshl_b32 s98, s98, 8
	v_mov_b32_e32 v1, s98
	v_mov_b32_e32 v3, s99
	v_mov_b32_e32 v4, 0
	v_mov_b32_e32 v2, 1
	global_load_dword v3, v3, s[6:7] offset:-2048 sc1
	global_atomic_add v4, v1, v2, s[6:7] sc0
	s_waitcnt vmcnt(0)
	v_readfirstlane_b32 s100, v3
	v_readfirstlane_b32 s99, v4
	s_mul_i32 s98, s100, 11
	s_add_i32 s99, s99, 1
	s_cmp_lg_u32 s99, s98
	s_cbranch_scc1 .Lxb_follow_s11
	buffer_wbl2 sc1
	s_waitcnt vmcnt(0)
	v_mov_b32_e32 v4, 0
	global_atomic_add v2, v4, v3, s[6:7] offset:-4096 sc0
	s_waitcnt vmcnt(0)
	v_readfirstlane_b32 s99, v2
	s_add_i32 s99, s99, s100
	s_mul_i32 s98, s40, 11
	v_mov_b32_e32 v2, 1
	s_cmp_lg_u32 s99, s98
	s_cbranch_scc1 .Lxb_topwait_s11
	global_atomic_add v4, v2, s[6:7] offset:-3840
	s_branch .Lxb_topdone_s11

.LBB0_1339:
	s_cmp_gt_i32 s39, 11
	s_cselect_b64 s[0:1], -1, 0
	s_and_b64 s[2:3], s[2:3], s[0:1]
	s_andn2_b64 vcc, exec, s[2:3]
	s_cbranch_vccnz .LBB0_1351
	v_and_b32_e32 v1, 0x3fffffff, v0
	v_cmp_eq_u32_e32 vcc, 0, v1
	s_waitcnt vmcnt(0) lgkmcnt(0)
	s_barrier
	s_and_saveexec_b64 s[4:5], vcc
	s_cbranch_execz .LBB0_1350
	s_add_u32 s6, s84, 0x2ce12000
	s_addc_u32 s7, s85, 0
	s_getreg_b32 s98, hwreg(HW_REG_XCC_ID, 0, 4)
	s_lshl_b32 s99, s98, 7
	s_lshl_b32 s98, s98, 8
	v_mov_b32_e32 v1, s98
	v_mov_b32_e32 v3, s99
	v_mov_b32_e32 v4, 0
	v_mov_b32_e32 v2, 1
	global_load_dword v3, v3, s[6:7] offset:-2048 sc1
	global_atomic_add v4, v1, v2, s[6:7] sc0
	s_waitcnt vmcnt(0)
	v_readfirstlane_b32 s100, v3
	v_readfirstlane_b32 s99, v4
	s_mul_i32 s98, s100, 12
	s_add_i32 s99, s99, 1
	s_cmp_lg_u32 s99, s98
	s_cbranch_scc1 .Lxb_follow_s12
	buffer_wbl2 sc1
	s_waitcnt vmcnt(0)
	v_mov_b32_e32 v4, 0
	global_atomic_add v2, v4, v3, s[6:7] offset:-4096 sc0
	s_waitcnt vmcnt(0)
	v_readfirstlane_b32 s99, v2
	s_add_i32 s99, s99, s100
	s_mul_i32 s98, s40, 12
	v_mov_b32_e32 v2, 1
	s_cmp_lg_u32 s99, s98
	s_cbranch_scc1 .Lxb_topwait_s12
	global_atomic_add v4, v2, s[6:7] offset:-3840
	s_branch .Lxb_topdone_s12

.Lxb_topspin_s12:
	global_load_dword v3, v4, s[6:7] offset:-3840 sc1
	s_waitcnt vmcnt(0)
	v_readfirstlane_b32 s99, v3
	s_cmp_ge_u32 s99, 12
	s_cbranch_scc1 .Lxb_topdone_s12
	s_sleep 1
	s_sub_u32 s101, s101, 1
	s_cmp_lg_u32 s101, 0
	s_cbranch_scc1 .Lxb_topspin_s12

.Lxb_spin_s12:
	global_load_dword v3, v1, s[6:7] offset:128 sc1
	s_waitcnt vmcnt(0)
	v_readfirstlane_b32 s99, v3
	s_cmp_ge_u32 s99, 12
	s_cbranch_scc1 .Lxb_rel_s12
	s_sleep 1
	s_sub_u32 s101, s101, 1
	s_cmp_lg_u32 s101, 0
	s_cbranch_scc1 .Lxb_spin_s12

.LBB0_1373:
	s_cmp_gt_i32 s39, 12
	s_cselect_b64 s[6:7], -1, 0
	s_and_b64 s[0:1], s[4:5], s[6:7]
	s_andn2_b64 vcc, exec, s[0:1]
	s_cbranch_vccnz .LBB0_1385
	v_and_b32_e32 v1, 0x3fffffff, v0
	v_cmp_eq_u32_e32 vcc, 0, v1
	s_waitcnt vmcnt(0) lgkmcnt(0)
	s_barrier
	s_and_saveexec_b64 s[0:1], vcc
	s_cbranch_execz .LBB0_1384
	s_add_u32 s4, s84, 0x2ce12000
	s_addc_u32 s5, s85, 0
	s_getreg_b32 s98, hwreg(HW_REG_XCC_ID, 0, 4)
	s_lshl_b32 s99, s98, 7
	s_lshl_b32 s98, s98, 8
	v_mov_b32_e32 v1, s98
	v_mov_b32_e32 v3, s99
	v_mov_b32_e32 v4, 0
	v_mov_b32_e32 v2, 1
	global_load_dword v3, v3, s[4:5] offset:-2048 sc1
	global_atomic_add v4, v1, v2, s[4:5] sc0
	s_waitcnt vmcnt(0)
	v_readfirstlane_b32 s100, v3
	v_readfirstlane_b32 s99, v4
	s_mul_i32 s98, s100, 13
	s_add_i32 s99, s99, 1
	s_cmp_lg_u32 s99, s98
	s_cbranch_scc1 .Lxb_follow_s13
	buffer_wbl2 sc1
	s_waitcnt vmcnt(0)
	v_mov_b32_e32 v4, 0
	global_atomic_add v2, v4, v3, s[4:5] offset:-4096 sc0
	s_waitcnt vmcnt(0)
	v_readfirstlane_b32 s99, v2
	s_add_i32 s99, s99, s100
	s_mul_i32 s98, s40, 13
	v_mov_b32_e32 v2, 1
	s_cmp_lg_u32 s99, s98
	s_cbranch_scc1 .Lxb_topwait_s13
	global_atomic_add v4, v2, s[4:5] offset:-3840
	s_branch .Lxb_topdone_s13

.LBB0_1395:
	s_cmp_gt_i32 s39, 13
	s_cselect_b64 s[6:7], -1, 0
	s_and_b64 s[0:1], s[0:1], s[6:7]
	s_andn2_b64 vcc, exec, s[0:1]
	s_cbranch_vccnz .LBB0_1407
	v_and_b32_e32 v1, 0x3fffffff, v0
	v_cmp_eq_u32_e32 vcc, 0, v1
	s_waitcnt vmcnt(0) lgkmcnt(0)
	s_barrier
	s_and_saveexec_b64 s[0:1], vcc
	s_cbranch_execz .LBB0_1406
	s_add_u32 s4, s84, 0x2ce12000
	s_addc_u32 s5, s85, 0
	s_getreg_b32 s98, hwreg(HW_REG_XCC_ID, 0, 4)
	s_lshl_b32 s99, s98, 7
	s_lshl_b32 s98, s98, 8
	v_mov_b32_e32 v1, s98
	v_mov_b32_e32 v3, s99
	v_mov_b32_e32 v4, 0
	v_mov_b32_e32 v2, 1
	global_load_dword v3, v3, s[4:5] offset:-2048 sc1
	global_atomic_add v4, v1, v2, s[4:5] sc0
	s_waitcnt vmcnt(0)
	v_readfirstlane_b32 s100, v3
	v_readfirstlane_b32 s99, v4
	s_mul_i32 s98, s100, 14
	s_add_i32 s99, s99, 1
	s_cmp_lg_u32 s99, s98
	s_cbranch_scc1 .Lxb_follow_s14
	buffer_wbl2 sc1
	s_waitcnt vmcnt(0)
	v_mov_b32_e32 v4, 0
	global_atomic_add v2, v4, v3, s[4:5] offset:-4096 sc0
	s_waitcnt vmcnt(0)
	v_readfirstlane_b32 s99, v2
	s_add_i32 s99, s99, s100
	s_mul_i32 s98, s40, 14
	v_mov_b32_e32 v2, 1
	s_cmp_lg_u32 s99, s98
	s_cbranch_scc1 .Lxb_topwait_s14
	global_atomic_add v4, v2, s[4:5] offset:-3840
	s_branch .Lxb_topdone_s14

.Lxb_topspin_s14:
	global_load_dword v3, v4, s[4:5] offset:-3840 sc1
	s_waitcnt vmcnt(0)
	v_readfirstlane_b32 s99, v3
	s_cmp_ge_u32 s99, 14
	s_cbranch_scc1 .Lxb_topdone_s14
	s_sleep 1
	s_sub_u32 s101, s101, 1
	s_cmp_lg_u32 s101, 0
	s_cbranch_scc1 .Lxb_topspin_s14

.Lxb_spin_s14:
	global_load_dword v3, v1, s[4:5] offset:128 sc1
	s_waitcnt vmcnt(0)
	v_readfirstlane_b32 s99, v3
	s_cmp_ge_u32 s99, 14
	s_cbranch_scc1 .Lxb_rel_s14
	s_sleep 1
	s_sub_u32 s101, s101, 1
	s_cmp_lg_u32 s101, 0
	s_cbranch_scc1 .Lxb_spin_s14

.LBB0_1429:
	s_cmp_gt_i32 s39, 14
	s_cselect_b64 s[0:1], -1, 0
	s_and_b64 s[2:3], s[4:5], s[0:1]
	s_andn2_b64 vcc, exec, s[2:3]
	s_cbranch_vccnz .LBB0_1441
	v_and_b32_e32 v1, 0x3fffffff, v0
	v_cmp_eq_u32_e32 vcc, 0, v1
	s_waitcnt vmcnt(0) lgkmcnt(0)
	s_barrier
	s_and_saveexec_b64 s[4:5], vcc
	s_cbranch_execz .LBB0_1440
	s_add_u32 s6, s84, 0x2ce12000
	s_addc_u32 s7, s85, 0
	s_getreg_b32 s98, hwreg(HW_REG_XCC_ID, 0, 4)
	s_lshl_b32 s99, s98, 7
	s_lshl_b32 s98, s98, 8
	v_mov_b32_e32 v1, s98
	v_mov_b32_e32 v3, s99
	v_mov_b32_e32 v4, 0
	v_mov_b32_e32 v2, 1
	global_load_dword v3, v3, s[6:7] offset:-2048 sc1
	global_atomic_add v4, v1, v2, s[6:7] sc0
	s_waitcnt vmcnt(0)
	v_readfirstlane_b32 s100, v3
	v_readfirstlane_b32 s99, v4
	s_mul_i32 s98, s100, 15
	s_add_i32 s99, s99, 1
	s_cmp_lg_u32 s99, s98
	s_cbranch_scc1 .Lxb_follow_s15
	buffer_wbl2 sc1
	s_waitcnt vmcnt(0)
	v_mov_b32_e32 v4, 0
	global_atomic_add v2, v4, v3, s[6:7] offset:-4096 sc0
	s_waitcnt vmcnt(0)
	v_readfirstlane_b32 s99, v2
	s_add_i32 s99, s99, s100
	s_mul_i32 s98, s40, 15
	v_mov_b32_e32 v2, 1
	s_cmp_lg_u32 s99, s98
	s_cbranch_scc1 .Lxb_topwait_s15
	global_atomic_add v4, v2, s[6:7] offset:-3840
	s_branch .Lxb_topdone_s15

.LBB0_1447:
	s_cmp_gt_i32 s39, 15
	s_cselect_b64 s[0:1], -1, 0
	s_and_b64 s[2:3], s[8:9], s[0:1]
	s_andn2_b64 vcc, exec, s[2:3]
	s_cbranch_vccnz .LBB0_1459
	v_and_b32_e32 v1, 0x3fffffff, v0
	v_cmp_eq_u32_e32 vcc, 0, v1
	s_waitcnt vmcnt(0) lgkmcnt(0)
	s_barrier
	s_and_saveexec_b64 s[4:5], vcc
	s_cbranch_execz .LBB0_1458
	s_add_u32 s6, s84, 0x2ce12000
	s_addc_u32 s7, s85, 0
	s_getreg_b32 s98, hwreg(HW_REG_XCC_ID, 0, 4)
	s_lshl_b32 s99, s98, 7
	s_lshl_b32 s98, s98, 8
	v_mov_b32_e32 v1, s98
	v_mov_b32_e32 v3, s99
	v_mov_b32_e32 v4, 0
	v_mov_b32_e32 v2, 1
	global_load_dword v3, v3, s[6:7] offset:-2048 sc1
	global_atomic_add v4, v1, v2, s[6:7] sc0
	s_waitcnt vmcnt(0)
	v_readfirstlane_b32 s100, v3
	v_readfirstlane_b32 s99, v4
	s_mul_i32 s98, s100, 16
	s_add_i32 s99, s99, 1
	s_cmp_lg_u32 s99, s98
	s_cbranch_scc1 .Lxb_follow_s16
	buffer_wbl2 sc1
	s_waitcnt vmcnt(0)
	v_mov_b32_e32 v4, 0
	global_atomic_add v2, v4, v3, s[6:7] offset:-4096 sc0
	s_waitcnt vmcnt(0)
	v_readfirstlane_b32 s99, v2
	s_add_i32 s99, s99, s100
	s_mul_i32 s98, s40, 16
	v_mov_b32_e32 v2, 1
	s_cmp_lg_u32 s99, s98
	s_cbranch_scc1 .Lxb_topwait_s16
	global_atomic_add v4, v2, s[6:7] offset:-3840
	s_branch .Lxb_topdone_s16

.Lxb_topspin_s16:
	global_load_dword v3, v4, s[6:7] offset:-3840 sc1
	s_waitcnt vmcnt(0)
	v_readfirstlane_b32 s99, v3
	s_cmp_ge_u32 s99, 16
	s_cbranch_scc1 .Lxb_topdone_s16
	s_sleep 1
	s_sub_u32 s101, s101, 1
	s_cmp_lg_u32 s101, 0
	s_cbranch_scc1 .Lxb_topspin_s16

.Lxb_spin_s16:
	global_load_dword v3, v1, s[6:7] offset:128 sc1
	s_waitcnt vmcnt(0)
	v_readfirstlane_b32 s99, v3
	s_cmp_ge_u32 s99, 16
	s_cbranch_scc1 .Lxb_rel_s16
	s_sleep 1
	s_sub_u32 s101, s101, 1
	s_cmp_lg_u32 s101, 0
	s_cbranch_scc1 .Lxb_spin_s16

.LBB0_1480:
	s_cmp_lg_u32 s82, 0
	s_cbranch_scc1 .Lxb_noreset
	v_and_b32_e32 v1, 0x3fffffff, v0
	v_cmp_eq_u32_e32 vcc, 0, v1
	s_and_saveexec_b64 s[98:99], vcc
	v_mov_b32_e32 v1, 0
	v_mov_b32_e32 v2, 0
	s_add_u32 s100, s84, 0x2ce11200
	s_addc_u32 s101, s85, 0
	global_atomic_swap v1, v2, s[100:101]
	s_or_b64 exec, exec, s[98:99]
